# phase 0 row norms: gain vector g_pre_mix loaded once before the row loop (conditional reload of g_mem for the memory rows) instead of after every store; removes 11 vmcnt(0) drains per iteration
# speedup vs baseline: 1.0135x; 1.0050x over previous
.LBB0_524:
	v_ashrrev_i32_e32 v0, 6, v200
	v_readlane_b32 s0, v251, 5
	s_nop 1
	v_add_u32_e32 v50, s0, v0
	s_movk_i32 s0, 0x4800
	v_cmp_gt_i32_e32 vcc, s0, v50
	s_and_saveexec_b64 s[8:9], vcc
	s_cbranch_execz .LBB0_531
	v_add_u32_e32 v1, 64, v220
	v_xor_b32_e32 v2, 32, v219
	v_cmp_lt_i32_e32 vcc, v2, v1
	s_load_dword s0, s[54:55], 0x10
	s_load_dword s2, s[54:55], 0x0
	v_cndmask_b32_e32 v2, v219, v2, vcc
	v_lshlrev_b32_e32 v49, 2, v2
	v_xor_b32_e32 v2, 16, v219
	v_cmp_lt_i32_e32 vcc, v2, v1
	s_waitcnt lgkmcnt(0)
	s_lshr_b32 s0, s0, 16
	s_cmp_lg_u32 s0, 0
	v_cndmask_b32_e32 v2, v219, v2, vcc
	v_lshlrev_b32_e32 v58, 2, v2
	v_xor_b32_e32 v2, 8, v219
	v_cmp_lt_i32_e32 vcc, v2, v1
	s_cselect_b64 s[0:1], -1, 0
	s_cmp_lg_u64 s[0:1], 0
	v_cndmask_b32_e32 v2, v219, v2, vcc
	v_lshlrev_b32_e32 v59, 2, v2
	v_xor_b32_e32 v2, 4, v219
	v_cmp_lt_i32_e32 vcc, v2, v1
	s_addc_u32 s2, s2, 0
	s_lshl_b32 s0, s2, 2
	v_cndmask_b32_e32 v2, v219, v2, vcc
	v_lshlrev_b32_e32 v60, 2, v2
	v_xor_b32_e32 v2, 2, v219
	v_cmp_lt_i32_e32 vcc, v2, v1
	v_lshlrev_b32_e32 v0, 2, v48
	s_mul_i32 s1, s2, 12
	v_cndmask_b32_e32 v2, v219, v2, vcc
	v_lshlrev_b32_e32 v61, 2, v2
	v_xor_b32_e32 v2, 1, v219
	v_cmp_lt_i32_e32 vcc, v2, v1
	v_add_u32_e32 v52, s0, v50
	s_lshl_b32 s2, s2, 3
	v_cndmask_b32_e32 v1, v219, v2, vcc
	v_lshlrev_b32_e32 v62, 2, v1
	v_ashrrev_i32_e32 v53, 31, v52
	s_ashr_i32 s14, s1, 31
	v_ashrrev_i32_e32 v51, 31, v50
	s_mov_b64 s[10:11], 0
	v_lshlrev_b32_e32 v54, 2, v0
	s_mov_b64 s[12:13], 0
	v_mov_b32_e32 v63, v50
	v_readlane_b32 s40, v249, 25
	v_readlane_b32 s41, v249, 26
	v_lshlrev_b32_e32 v94, 4, v48
	s_nop 4
	global_load_dwordx4 v[76:79], v94, s[40:41]
	global_load_dwordx4 v[82:85], v94, s[40:41] offset:1024
	global_load_dwordx4 v[86:89], v94, s[40:41] offset:2048
	global_load_dwordx4 v[90:93], v94, s[40:41] offset:3072
	s_branch .LBB0_527

.LBB0_527:
	v_readlane_b32 s4, v249, 27
	v_add_u32_e32 v2, 0xffffc000, v63
	v_lshl_add_u64 v[0:1], v[50:51], 0, s[12:13]
	v_cmp_gt_i32_e32 vcc, s33, v63
	v_readlane_b32 s5, v249, 28
	v_readlane_b32 s6, v249, 29
	v_readlane_b32 s7, v249, 30
	v_cndmask_b32_e32 v1, 0, v1, vcc
	v_cndmask_b32_e32 v0, v2, v0, vcc
	v_mov_b32_e32 v36, s7
	v_mov_b32_e32 v37, s5
	v_mov_b32_e32 v38, s6
	v_mov_b32_e32 v39, s4
	v_cndmask_b32_e32 v3, v36, v37, vcc
	v_cndmask_b32_e32 v2, v38, v39, vcc
	v_lshlrev_b64 v[4:5], 12, v[0:1]
	v_lshl_add_u64 v[2:3], v[2:3], 0, v[4:5]
	v_mov_b32_e32 v55, v197
	v_lshl_add_u64 v[2:3], v[2:3], 0, v[54:55]
	global_load_dwordx4 v[28:31], v[2:3], off nt
	global_load_dwordx4 v[24:27], v[2:3], off offset:1024 nt
	global_load_dwordx4 v[20:23], v[2:3], off offset:2048 nt
	global_load_dwordx4 v[16:19], v[2:3], off offset:3072 nt
	v_readlane_b32 s4, v249, 21
	v_readlane_b32 s6, v249, 25
	v_readlane_b32 s5, v249, 22
	v_readlane_b32 s7, v249, 26
	v_mov_b32_e32 v4, s4
	v_mov_b32_e32 v2, s5
	v_mov_b32_e32 v3, s7
	v_mov_b32_e32 v5, s6
	v_lshlrev_b32_e32 v196, 4, v48
	v_cndmask_b32_e32 v3, v2, v3, vcc
	v_cndmask_b32_e32 v2, v4, v5, vcc
	s_waitcnt vmcnt(0)
	v_lshl_add_u64 v[70:71], v[2:3], 0, v[196:197]
	s_cbranch_vccnz .Lp0g_0
	global_load_dwordx4 v[76:79], v[70:71], off
	global_load_dwordx4 v[82:85], v[70:71], off offset:1024
	global_load_dwordx4 v[86:89], v[70:71], off offset:2048
	global_load_dwordx4 v[90:93], v[70:71], off offset:3072
	s_waitcnt vmcnt(0)
.Lp0g_0:
	v_readlane_b32 s16, v250, 53
	v_readlane_b32 s23, v250, 60
	v_mov_b32_e32 v6, s57
	v_readlane_b32 s22, v250, 59
	v_mov_b32_e32 v7, s23
	v_cndmask_b32_e32 v5, v6, v7, vcc
	v_mov_b32_e32 v8, s56
	v_mov_b32_e32 v9, s22
	v_cndmask_b32_e32 v4, v8, v9, vcc
	v_add_u32_e32 v65, s0, v63
	s_movk_i32 s6, 0x4800
	v_add_u32_e32 v64, s2, v63
	v_cmp_gt_i32_e64 s[4:5], s6, v65
	v_cmp_gt_i32_e32 vcc, s6, v64
	v_lshlrev_b64 v[0:1], 11, v[0:1]
	v_cndmask_b32_e64 v40, v63, v65, s[4:5]
	v_cndmask_b32_e32 v41, v63, v64, vcc
	v_ashrrev_i32_e32 v42, 31, v40
	v_cmp_gt_i32_e64 s[6:7], s33, v40
	v_lshl_add_u64 v[0:1], v[4:5], 0, v[0:1]
	v_lshlrev_b32_e32 v56, 3, v48
	v_cndmask_b32_e64 v5, v36, v37, s[6:7]
	v_cndmask_b32_e64 v4, v38, v39, s[6:7]
	v_mov_b32_e32 v57, v197
	v_lshl_add_u64 v[72:73], v[0:1], 0, v[56:57]
	v_readlane_b32 s17, v250, 54
	v_readlane_b32 s18, v250, 55
	v_readlane_b32 s19, v250, 56
	v_readlane_b32 s20, v250, 57
	v_readlane_b32 s21, v250, 58
	v_readlane_b32 s24, v250, 61
	v_readlane_b32 s25, v250, 62
	v_readlane_b32 s26, v250, 63
	v_readlane_b32 s27, v249, 0
	v_readlane_b32 s28, v249, 1
	v_readlane_b32 s29, v249, 2
	v_readlane_b32 s30, v249, 3
	v_readlane_b32 s31, v249, 4
	v_mov_b32_e32 v6, v29
	v_mov_b32_e32 v7, v25
	v_mov_b32_e32 v2, v28
	v_mov_b32_e32 v3, v24
	v_mov_b32_e32 v14, v21
	v_mov_b32_e32 v15, v17
	v_pk_mul_f32 v[6:7], v[6:7], v[6:7]
	v_mov_b32_e32 v8, v30
	v_mov_b32_e32 v9, v26
	v_mov_b32_e32 v12, v20
	v_mov_b32_e32 v13, v16
	v_pk_mul_f32 v[14:15], v[14:15], v[14:15]
	v_pk_fma_f32 v[2:3], v[2:3], v[2:3], v[6:7]
	v_mov_b32_e32 v10, v31
	v_mov_b32_e32 v11, v27
	v_mov_b32_e32 v32, v22
	v_mov_b32_e32 v33, v18
	v_pk_fma_f32 v[6:7], v[12:13], v[12:13], v[14:15]
	v_pk_fma_f32 v[2:3], v[8:9], v[8:9], v[2:3]
	v_mov_b32_e32 v34, v23
	v_mov_b32_e32 v35, v19
	v_pk_fma_f32 v[6:7], v[32:33], v[32:33], v[6:7]
	v_pk_fma_f32 v[2:3], v[10:11], v[10:11], v[2:3]
	v_pk_fma_f32 v[6:7], v[34:35], v[34:35], v[6:7]
	v_add_f32_e32 v2, v2, v3
	v_add_f32_e32 v2, v2, v6
	v_add_f32_e32 v2, v2, v7
	v_mov_b32_e32 v3, v2
	v_mov_b32_e32 v184, v2
	s_nop 1
	v_permlane32_swap_b32_e32 v3, v184
	v_add_u32_e32 v6, 0xffffc000, v40
	v_ashrrev_i32_e32 v7, 31, v41
	v_add_u32_e32 v8, 0xffffc000, v41
	s_waitcnt lgkmcnt(0)
	v_add_f32_e32 v9, v3, v184
	v_mov_b32_e32 v10, v9
	v_mov_b32_e32 v185, v9
	s_nop 1
	v_permlane16_swap_b32_e32 v10, v185
	v_cndmask_b32_e64 v3, 0, v42, s[6:7]
	v_cndmask_b32_e64 v2, v6, v40, s[6:7]
	v_cmp_gt_i32_e64 s[6:7], s33, v41
	v_lshlrev_b64 v[0:1], 12, v[2:3]
	s_waitcnt lgkmcnt(0)
	v_add_f32_e32 v10, v10, v185
	s_nop 1
	v_mov_b32_dpp v11, v10 row_ror:8 row_mask:0xf bank_mask:0xf
	v_cndmask_b32_e64 v7, 0, v7, s[6:7]
	v_cndmask_b32_e64 v6, v8, v41, s[6:7]
	v_lshlrev_b64 v[2:3], 12, v[6:7]
	v_lshl_add_u64 v[0:1], v[4:5], 0, v[0:1]
	s_waitcnt lgkmcnt(0)
	v_add_f32_e32 v10, v10, v11
	s_nop 1
	v_mov_b32_dpp v11, v10 row_ror:4 row_mask:0xf bank_mask:0xa
	v_mov_b32_dpp v11, v10 row_ror:12 row_mask:0xf bank_mask:0x5
	v_lshl_add_u64 v[0:1], v[0:1], 0, v[54:55]
	v_cndmask_b32_e64 v9, v36, v37, s[6:7]
	v_cndmask_b32_e64 v8, v38, v39, s[6:7]
	global_load_dwordx4 v[44:47], v[0:1], off nt
	global_load_dwordx4 v[40:43], v[0:1], off offset:1024 nt
	global_load_dwordx4 v[36:39], v[0:1], off offset:2048 nt
	global_load_dwordx4 v[32:35], v[0:1], off offset:3072 nt
	s_waitcnt lgkmcnt(0)
	v_add_f32_e32 v6, v10, v11
	s_nop 1
	v_mov_b32_dpp v7, v6 quad_perm:[2,3,0,1] row_mask:0xf bank_mask:0xf
	v_lshl_add_u64 v[2:3], v[8:9], 0, v[2:3]
	v_lshl_add_u64 v[2:3], v[2:3], 0, v[54:55]
	s_waitcnt lgkmcnt(0)
	v_add_f32_e32 v4, v6, v7
	s_nop 1
	v_mov_b32_dpp v5, v4 quad_perm:[1,0,3,2] row_mask:0xf bank_mask:0xf
	s_waitcnt lgkmcnt(0)
	v_add_f32_e32 v0, v4, v5
	v_fmamk_f32 v0, v0, 0x3a800000, v198
	v_mul_f32_e32 v1, 0x4b800000, v0
	v_cmp_gt_f32_e64 s[6:7], s51, v0
	s_nop 1
	v_cndmask_b32_e64 v0, v0, v1, s[6:7]
	v_rsq_f32_e32 v55, v0
	global_load_dwordx4 v[12:15], v[2:3], off nt
	global_load_dwordx4 v[8:11], v[2:3], off offset:1024 nt
	global_load_dwordx4 v[4:7], v[2:3], off offset:2048 nt
	s_nop 0
	global_load_dwordx4 v[0:3], v[2:3], off offset:3072 nt
	v_mul_f32_e32 v74, 0x45800000, v55
	v_cndmask_b32_e64 v74, v55, v74, s[6:7]
	v_pk_mul_f32 v[28:29], v[28:29], v[74:75] op_sel_hi:[1,0]
	v_pk_mul_f32 v[30:31], v[30:31], v[74:75] op_sel_hi:[1,0]
	s_waitcnt vmcnt(8)
	v_pk_mul_f32 v[28:29], v[76:77], v[28:29]
	v_pk_mul_f32 v[30:31], v[78:79], v[30:31]
	v_cvt_pk_bf16_f32 v28, v28, v29
	v_cvt_pk_bf16_f32 v29, v30, v31
	global_store_dwordx2 v[72:73], v[28:29], off
	v_pk_mul_f32 v[24:25], v[24:25], v[74:75] op_sel_hi:[1,0]
	v_pk_mul_f32 v[26:27], v[26:27], v[74:75] op_sel_hi:[1,0]
	v_pk_mul_f32 v[20:21], v[20:21], v[74:75] op_sel_hi:[1,0]
	v_pk_mul_f32 v[22:23], v[22:23], v[74:75] op_sel_hi:[1,0]
	v_pk_mul_f32 v[16:17], v[16:17], v[74:75] op_sel_hi:[1,0]
	v_pk_mul_f32 v[18:19], v[18:19], v[74:75] op_sel_hi:[1,0]
	v_pk_mul_f32 v[24:25], v[82:83], v[24:25]
	v_pk_mul_f32 v[26:27], v[84:85], v[26:27]
	v_cvt_pk_bf16_f32 v24, v24, v25
	v_cvt_pk_bf16_f32 v25, v26, v27
	global_store_dwordx2 v[72:73], v[24:25], off offset:512
	v_pk_mul_f32 v[20:21], v[20:21], v[86:87]
	v_pk_mul_f32 v[22:23], v[22:23], v[88:89]
	v_cvt_pk_bf16_f32 v20, v20, v21
	v_cvt_pk_bf16_f32 v21, v22, v23
	global_store_dwordx2 v[72:73], v[20:21], off offset:1024
	v_pk_mul_f32 v[16:17], v[16:17], v[90:91]
	v_pk_mul_f32 v[18:19], v[18:19], v[92:93]
	v_cvt_pk_bf16_f32 v16, v16, v17
	v_cvt_pk_bf16_f32 v17, v18, v19
	global_store_dwordx2 v[72:73], v[16:17], off offset:1536
	s_and_saveexec_b64 s[6:7], s[4:5]
	s_cbranch_execz .LBB0_529
	s_waitcnt vmcnt(0)
	v_readlane_b32 s16, v249, 21
	v_readlane_b32 s18, v249, 25
	v_readlane_b32 s17, v249, 22
	v_readlane_b32 s19, v249, 26
	v_cmp_gt_i32_e64 s[4:5], s33, v65
	v_mov_b32_e32 v16, s17
	v_mov_b32_e32 v17, s19
	v_cndmask_b32_e64 v17, v16, v17, s[4:5]
	v_mov_b32_e32 v16, s16
	v_mov_b32_e32 v18, s18
	v_cndmask_b32_e64 v16, v16, v18, s[4:5]
	v_lshl_add_u64 v[20:21], v[16:17], 0, v[196:197]
	s_and_b64 s[40:41], exec, s[4:5]
	s_cbranch_scc1 .Lp0g_1
	global_load_dwordx4 v[76:79], v[20:21], off
	global_load_dwordx4 v[82:85], v[20:21], off offset:1024
	global_load_dwordx4 v[86:89], v[20:21], off offset:2048
	global_load_dwordx4 v[90:93], v[20:21], off offset:3072
	s_waitcnt vmcnt(0)
.Lp0g_1:
	v_mov_b32_e32 v24, v45
	v_mov_b32_e32 v25, v41
	v_mov_b32_e32 v22, v44
	v_mov_b32_e32 v23, v40
	v_pk_mul_f32 v[24:25], v[24:25], v[24:25]
	v_mov_b32_e32 v26, v37
	v_pk_fma_f32 v[22:23], v[22:23], v[22:23], v[24:25]
	v_mov_b32_e32 v24, v46
	v_mov_b32_e32 v25, v42
	v_pk_fma_f32 v[22:23], v[24:25], v[24:25], v[22:23]
	v_mov_b32_e32 v24, v47
	v_mov_b32_e32 v25, v43
	v_mov_b32_e32 v27, v33
	v_pk_fma_f32 v[22:23], v[24:25], v[24:25], v[22:23]
	v_mov_b32_e32 v24, v36
	v_mov_b32_e32 v25, v32
	v_pk_mul_f32 v[26:27], v[26:27], v[26:27]
	v_add_f32_e32 v22, v22, v23
	v_pk_fma_f32 v[24:25], v[24:25], v[24:25], v[26:27]
	v_mov_b32_e32 v26, v38
	v_mov_b32_e32 v27, v34
	v_pk_fma_f32 v[24:25], v[26:27], v[26:27], v[24:25]
	v_mov_b32_e32 v26, v39
	v_mov_b32_e32 v27, v35
	v_pk_fma_f32 v[24:25], v[26:27], v[26:27], v[24:25]
	v_add_u32_e32 v26, 0xffffc000, v65
	v_add_f32_e32 v22, v22, v24
	v_add_f32_e32 v22, v22, v25
	v_mov_b32_e32 v23, v22
	v_mov_b32_e32 v186, v22
	s_nop 1
	v_permlane32_swap_b32_e32 v23, v186
	v_readlane_b32 s16, v250, 53
	v_readlane_b32 s22, v250, 59
	v_readlane_b32 s23, v250, 60
	v_mov_b32_e32 v27, s57
	s_waitcnt lgkmcnt(0)
	v_add_f32_e32 v22, v23, v186
	v_mov_b32_e32 v23, v22
	v_mov_b32_e32 v187, v22
	s_nop 1
	v_permlane16_swap_b32_e32 v23, v187
	v_mov_b32_e32 v28, s23
	v_mov_b32_e32 v29, s56
	v_mov_b32_e32 v30, s22
	v_readlane_b32 s17, v250, 54
	s_waitcnt lgkmcnt(0)
	v_add_f32_e32 v22, v23, v187
	s_nop 1
	v_mov_b32_dpp v23, v22 row_ror:8 row_mask:0xf bank_mask:0xf
	v_readlane_b32 s18, v250, 55
	v_readlane_b32 s19, v250, 56
	v_readlane_b32 s20, v250, 57
	v_readlane_b32 s21, v250, 58
	s_waitcnt lgkmcnt(0)
	v_add_f32_e32 v24, v22, v23
	s_nop 1
	v_mov_b32_dpp v25, v24 row_ror:4 row_mask:0xf bank_mask:0xa
	v_mov_b32_dpp v25, v24 row_ror:12 row_mask:0xf bank_mask:0x5
	v_lshl_add_u64 v[22:23], v[52:53], 0, s[12:13]
	v_cndmask_b32_e64 v22, v26, v22, s[4:5]
	v_cndmask_b32_e64 v23, 0, v23, s[4:5]
	v_lshlrev_b64 v[22:23], 11, v[22:23]
	s_waitcnt lgkmcnt(0)
	v_add_f32_e32 v24, v24, v25
	s_nop 1
	v_mov_b32_dpp v25, v24 quad_perm:[2,3,0,1] row_mask:0xf bank_mask:0xf
	v_readlane_b32 s24, v250, 61
	v_readlane_b32 s25, v250, 62
	v_readlane_b32 s26, v250, 63
	v_readlane_b32 s27, v249, 0
	s_waitcnt lgkmcnt(0)
	v_add_f32_e32 v31, v24, v25
	s_nop 1
	v_mov_b32_dpp v55, v31 quad_perm:[1,0,3,2] row_mask:0xf bank_mask:0xf
	v_cndmask_b32_e64 v25, v27, v28, s[4:5]
	v_cndmask_b32_e64 v24, v29, v30, s[4:5]
	v_lshl_add_u64 v[22:23], v[24:25], 0, v[22:23]
	v_lshl_add_u64 v[22:23], v[22:23], 0, v[56:57]
	s_waitcnt lgkmcnt(0)
	v_add_f32_e32 v26, v31, v55
	v_fmamk_f32 v26, v26, 0x3a800000, v198
	v_mul_f32_e32 v27, 0x4b800000, v26
	v_cmp_gt_f32_e64 s[4:5], s51, v26
	v_readlane_b32 s28, v249, 1
	v_readlane_b32 s29, v249, 2
	v_cndmask_b32_e64 v26, v26, v27, s[4:5]
	v_rsq_f32_e32 v26, v26
	v_readlane_b32 s30, v249, 3
	v_readlane_b32 s31, v249, 4
	v_mul_f32_e32 v24, 0x45800000, v26
	v_cndmask_b32_e64 v24, v26, v24, s[4:5]
	v_pk_mul_f32 v[26:27], v[44:45], v[24:25] op_sel_hi:[1,0]
	v_pk_mul_f32 v[28:29], v[46:47], v[24:25] op_sel_hi:[1,0]
	v_pk_mul_f32 v[16:17], v[76:77], v[26:27]
	v_pk_mul_f32 v[18:19], v[78:79], v[28:29]
	v_cvt_pk_bf16_f32 v16, v16, v17
	v_cvt_pk_bf16_f32 v17, v18, v19
	global_store_dwordx2 v[22:23], v[16:17], off
	v_pk_mul_f32 v[26:27], v[40:41], v[24:25] op_sel_hi:[1,0]
	v_pk_mul_f32 v[28:29], v[42:43], v[24:25] op_sel_hi:[1,0]
	v_pk_mul_f32 v[16:17], v[82:83], v[26:27]
	v_pk_mul_f32 v[18:19], v[84:85], v[28:29]
	v_cvt_pk_bf16_f32 v16, v16, v17
	v_cvt_pk_bf16_f32 v17, v18, v19
	global_store_dwordx2 v[22:23], v[16:17], off offset:512
	v_pk_mul_f32 v[26:27], v[36:37], v[24:25] op_sel_hi:[1,0]
	v_pk_mul_f32 v[28:29], v[38:39], v[24:25] op_sel_hi:[1,0]
	v_pk_mul_f32 v[16:17], v[26:27], v[86:87]
	v_pk_mul_f32 v[18:19], v[28:29], v[88:89]
	v_cvt_pk_bf16_f32 v16, v16, v17
	v_cvt_pk_bf16_f32 v17, v18, v19
	global_store_dwordx2 v[22:23], v[16:17], off offset:1024
	v_pk_mul_f32 v[20:21], v[32:33], v[24:25] op_sel_hi:[1,0]
	v_pk_mul_f32 v[24:25], v[34:35], v[24:25] op_sel_hi:[1,0]
	v_pk_mul_f32 v[16:17], v[20:21], v[90:91]
	v_pk_mul_f32 v[18:19], v[24:25], v[92:93]
	v_cvt_pk_bf16_f32 v16, v16, v17
	v_cvt_pk_bf16_f32 v17, v18, v19
	global_store_dwordx2 v[22:23], v[16:17], off offset:1536
.LBB0_529:
	s_or_b64 exec, exec, s[6:7]
	s_and_saveexec_b64 s[4:5], vcc
	s_cbranch_execz .LBB0_526
	s_waitcnt vmcnt(0)
	v_readlane_b32 s6, v249, 21
	v_readlane_b32 s16, v249, 25
	v_readlane_b32 s7, v249, 22
	v_readlane_b32 s17, v249, 26
	v_cmp_gt_i32_e32 vcc, s33, v64
	v_mov_b32_e32 v16, s7
	v_mov_b32_e32 v17, s17
	v_cndmask_b32_e32 v17, v16, v17, vcc
	v_mov_b32_e32 v16, s6
	v_mov_b32_e32 v18, s16
	v_cndmask_b32_e32 v16, v16, v18, vcc
	v_lshl_add_u64 v[20:21], v[16:17], 0, v[196:197]
	s_cbranch_vccnz .Lp0g_2
	global_load_dwordx4 v[76:79], v[20:21], off
	global_load_dwordx4 v[82:85], v[20:21], off offset:1024
	global_load_dwordx4 v[86:89], v[20:21], off offset:2048
	global_load_dwordx4 v[90:93], v[20:21], off offset:3072
	s_waitcnt vmcnt(0)
.Lp0g_2:
	v_mov_b32_e32 v24, v13
	v_mov_b32_e32 v25, v9
	v_mov_b32_e32 v22, v12
	v_mov_b32_e32 v23, v8
	v_pk_mul_f32 v[24:25], v[24:25], v[24:25]
	v_mov_b32_e32 v26, v14
	v_mov_b32_e32 v27, v10
	v_pk_fma_f32 v[22:23], v[22:23], v[22:23], v[24:25]
	v_mov_b32_e32 v28, v15
	v_pk_fma_f32 v[22:23], v[26:27], v[26:27], v[22:23]
	v_mov_b32_e32 v26, v5
	v_mov_b32_e32 v27, v1
	v_mov_b32_e32 v29, v11
	v_mov_b32_e32 v24, v4
	v_mov_b32_e32 v25, v0
	v_pk_mul_f32 v[26:27], v[26:27], v[26:27]
	v_pk_fma_f32 v[22:23], v[28:29], v[28:29], v[22:23]
	v_mov_b32_e32 v28, v6
	v_mov_b32_e32 v29, v2
	v_pk_fma_f32 v[24:25], v[24:25], v[24:25], v[26:27]
	v_mov_b32_e32 v30, v7
	v_mov_b32_e32 v31, v3
	v_pk_fma_f32 v[24:25], v[28:29], v[28:29], v[24:25]
	v_add_f32_e32 v22, v22, v23
	v_pk_fma_f32 v[24:25], v[30:31], v[30:31], v[24:25]
	v_readlane_b32 s16, v250, 53
	v_add_f32_e32 v22, v22, v24
	v_add_f32_e32 v22, v22, v25
	v_mov_b32_e32 v23, v22
	v_mov_b32_e32 v188, v22
	s_nop 1
	v_permlane32_swap_b32_e32 v23, v188
	v_readlane_b32 s23, v250, 60
	v_add_u32_e32 v25, 0xffffc000, v64
	v_mov_b32_e32 v26, s57
	v_mov_b32_e32 v27, s23
	s_waitcnt lgkmcnt(0)
	v_add_f32_e32 v22, v23, v188
	v_mov_b32_e32 v23, v22
	v_mov_b32_e32 v189, v22
	s_nop 1
	v_permlane16_swap_b32_e32 v23, v189
	v_readlane_b32 s22, v250, 59
	v_ashrrev_i32_e32 v24, 31, v64
	v_mov_b32_e32 v28, s56
	v_mov_b32_e32 v29, s22
	s_waitcnt lgkmcnt(0)
	v_add_f32_e32 v22, v23, v189
	s_nop 1
	v_mov_b32_dpp v23, v22 row_ror:8 row_mask:0xf bank_mask:0xf
	v_mov_b32_e32 v57, v197
	v_readlane_b32 s17, v250, 54
	v_readlane_b32 s18, v250, 55
	v_readlane_b32 s19, v250, 56
	s_waitcnt lgkmcnt(0)
	v_add_f32_e32 v22, v22, v23
	s_nop 1
	v_mov_b32_dpp v23, v22 row_ror:4 row_mask:0xf bank_mask:0xa
	v_mov_b32_dpp v23, v22 row_ror:12 row_mask:0xf bank_mask:0x5
	v_readlane_b32 s20, v250, 57
	v_readlane_b32 s21, v250, 58
	v_readlane_b32 s24, v250, 61
	v_readlane_b32 s25, v250, 62
	s_waitcnt lgkmcnt(0)
	v_add_f32_e32 v22, v22, v23
	s_nop 1
	v_mov_b32_dpp v23, v22 quad_perm:[2,3,0,1] row_mask:0xf bank_mask:0xf
	v_readlane_b32 s26, v250, 63
	v_readlane_b32 s27, v249, 0
	v_readlane_b32 s28, v249, 1
	v_readlane_b32 s29, v249, 2
	s_waitcnt lgkmcnt(0)
	v_add_f32_e32 v30, v22, v23
	s_nop 1
	v_mov_b32_dpp v31, v30 quad_perm:[1,0,3,2] row_mask:0xf bank_mask:0xf
	v_cndmask_b32_e32 v22, v25, v64, vcc
	v_cndmask_b32_e32 v25, v26, v27, vcc
	v_cndmask_b32_e32 v23, 0, v24, vcc
	v_cndmask_b32_e32 v24, v28, v29, vcc
	s_waitcnt lgkmcnt(0)
	v_add_f32_e32 v26, v30, v31
	v_fmamk_f32 v26, v26, 0x3a800000, v198
	v_mul_f32_e32 v27, 0x4b800000, v26
	v_cmp_gt_f32_e32 vcc, s51, v26
	v_lshlrev_b64 v[22:23], 11, v[22:23]
	v_lshl_add_u64 v[22:23], v[24:25], 0, v[22:23]
	v_cndmask_b32_e32 v26, v26, v27, vcc
	v_rsq_f32_e32 v26, v26
	v_lshl_add_u64 v[22:23], v[22:23], 0, v[56:57]
	v_readlane_b32 s30, v249, 3
	v_readlane_b32 s31, v249, 4
	v_mul_f32_e32 v24, 0x45800000, v26
	v_cndmask_b32_e32 v24, v26, v24, vcc
	v_pk_mul_f32 v[12:13], v[12:13], v[24:25] op_sel_hi:[1,0]
	v_pk_mul_f32 v[14:15], v[14:15], v[24:25] op_sel_hi:[1,0]
	v_pk_mul_f32 v[8:9], v[8:9], v[24:25] op_sel_hi:[1,0]
	v_pk_mul_f32 v[12:13], v[76:77], v[12:13]
	v_pk_mul_f32 v[14:15], v[78:79], v[14:15]
	v_cvt_pk_bf16_f32 v12, v12, v13
	v_cvt_pk_bf16_f32 v13, v14, v15
	global_store_dwordx2 v[22:23], v[12:13], off
	v_pk_mul_f32 v[10:11], v[10:11], v[24:25] op_sel_hi:[1,0]
	v_pk_mul_f32 v[4:5], v[4:5], v[24:25] op_sel_hi:[1,0]
	v_pk_mul_f32 v[6:7], v[6:7], v[24:25] op_sel_hi:[1,0]
	v_pk_mul_f32 v[0:1], v[0:1], v[24:25] op_sel_hi:[1,0]
	v_pk_mul_f32 v[2:3], v[2:3], v[24:25] op_sel_hi:[1,0]
	v_pk_mul_f32 v[8:9], v[82:83], v[8:9]
	v_pk_mul_f32 v[10:11], v[84:85], v[10:11]
	v_cvt_pk_bf16_f32 v8, v8, v9
	v_cvt_pk_bf16_f32 v9, v10, v11
	global_store_dwordx2 v[22:23], v[8:9], off offset:512
	v_pk_mul_f32 v[4:5], v[4:5], v[86:87]
	v_pk_mul_f32 v[6:7], v[6:7], v[88:89]
	v_cvt_pk_bf16_f32 v4, v4, v5
	v_cvt_pk_bf16_f32 v5, v6, v7
	global_store_dwordx2 v[22:23], v[4:5], off offset:1024
	v_pk_mul_f32 v[0:1], v[0:1], v[90:91]
	v_pk_mul_f32 v[2:3], v[2:3], v[92:93]
	v_cvt_pk_bf16_f32 v0, v0, v1
	v_cvt_pk_bf16_f32 v1, v2, v3
	global_store_dwordx2 v[22:23], v[0:1], off offset:1536
	s_branch .LBB0_526
